# GEMM tile latch: end-of-tile barrier no longer drains the tile's global stores (grid barrier drains them); next-tile head store-WAR waits removed
# speedup vs baseline: 1.0175x; 1.0015x over previous
; DEVI void gemm_tile(const GJob& jb, int brow, int bcol, unsigned char* shm_) {
;     ...
;         gemm_epi(jb, brow + ai * HALF + wr * 64 + m * 16 + fr, bcol + bj * HALF + wc * 32 + fq * 8, acc[ai][bj][m][0], acc[ai][bj][m][1]);
;   __syncthreads();
;     ...
; }
; DEVI void gemm_job(const GJob& jb, int& cursor, int c, int G, unsigned char* lds) {
;   const int nM = T / BM, nN = jb.N / BM, ntile = nM * nN;
;   if (c >= 0) {
;     const int slot = ((G & 7) == 0) ? (c & 7) * (G >> 3) + (c >> 3) : c;
;     int first = (slot - cursor % G + G) % G;
;     for (int i = first; i < ntile; i += G) {
;       const int nig = WGM * nN, gid = i / nig, fm = gid * WGM, gsz = (nM - fm) < WGM ? (nM - fm) : WGM;
;       const int pm = fm + ((i % nig) % gsz), pn = (i % nig) / gsz;
;       gemm_tile(jb, pm * BM, pn * BM, lds);
.LBB0_409:
	s_waitcnt lgkmcnt(0)
	s_cmp_eq_u32 s98, 0
	s_cbranch_scc1 .Lmix_latch_static
	s_barrier
	v_readfirstlane_b32 s99, v169
	s_cmp_ge_u32 s99, 64
	s_cbranch_scc1 .Lmixf_wait_b
	s_mov_b64 exec, 1
	v_mov_b32_e32 v2, 1
	global_atomic_add v3, v1, v2, s[100:101] sc0
	s_waitcnt vmcnt(0)
	ds_write_b32 v1, v3 offset:8
	s_waitcnt lgkmcnt(0)
	s_mov_b64 exec, -1

; #define STAGE(bufoff,gbase,voff) do{ _Pragma("unroll") for(int _i=0;_i<2;++_i) \
;     __builtin_amdgcn_global_load_lds((const unsigned*)((const char*)(gbase)+(voff)[_i]),(LAS unsigned*)(lds+(bufoff)+ldsw+_i*8192),16,0,0);}while(0)
; DEVI void gemm_tile(const GJob& jb, int brow, int bcol, unsigned char* shm_) {
;     ...
;   for (int i = 0; i < 2; ++i) { int R, C; stage_rc(tid * 16 + i * 8192, R, C); const int Rb = (R & ~31) + perm32(R & 31); voffA[i] = (unsigned)(R * lda + C) * 2u; voffB[i] = (unsigned)(Rb * ldb + C) * 2u; }
;   const size_t hA = (size_t)HALF * lda * 2, hB = (size_t)HALF * ldb * 2;
;   const unsigned ldsw = (unsigned)wid * 1024u;
;   const int aoff = lds_byte(wr * 64 + fr, fq * 8), boff = lds_byte(wc * 32 + fr, fq * 8);
;   constexpr int HTB = HT * 2;
;     ...
;   f32x4 acc[2][2][4][2];
; #pragma unroll
;   for (int a = 0; a < 2; ++a)
; #pragma unroll
;     for (int b = 0; b < 2; ++b)
; #pragma unroll
;       for (int m = 0; m < 4; ++m)
; #pragma unroll
;         for (int n = 0; n < 2; ++n) acc[a][b][m][n] = (f32x4){0.f, 0.f, 0.f, 0.f};
;   bf16x8 At[4][2], B0[2][2], B1[2][2];
;   const int nt = K / BK;
;   const char* cA = (const char*)jb.A + (size_t)brow * lda * 2; const char* cB = (const char*)jb.Bt + (size_t)bcol * ldb * 2;
;   STAGE(SB(0,0),cB,voffB); STAGE(SA(0,0),cA,voffA);
;   STAGE(SB(0,1),cB+hB,voffB); STAGE(SA(0,1),cA+hA,voffA);
; DEVI void gemm_job(const GJob& jb, int& cursor, int c, int G, unsigned char* lds) {
;     ...
;       const int nig = WGM * nN, gid = i / nig, fm = gid * WGM, gsz = (nM - fm) < WGM ? (nM - fm) : WGM;
;       const int pm = fm + ((i % nig) % gsz), pn = (i % nig) / gsz;
;       gemm_tile(jb, pm * BM, pn * BM, lds);
.LBB0_410:
	s_abs_i32 s1, s20
	s_mul_hi_u32 s4, s1, s48
	s_mul_i32 s5, s4, s14
	s_ashr_i32 s0, s20, 31
	s_sub_i32 s1, s1, s5
	s_xor_b32 s0, s0, s15
	s_add_i32 s5, s4, 1
	s_sub_i32 s8, s1, s14
	s_cmp_ge_u32 s1, s14
	s_cselect_b32 s4, s5, s4
	s_cselect_b32 s1, s8, s1
	s_add_i32 s5, s4, 1
	s_cmp_ge_u32 s1, s14
	s_cselect_b32 s1, s5, s4
	s_xor_b32 s1, s1, s0
	s_sub_i32 s5, s1, s0
	s_lshl_b32 s4, s5, 3
	s_sub_i32 s8, 32, s4
	s_min_i32 s8, s8, 8
	s_abs_i32 s9, s8
	v_cvt_f32_u32_e32 v0, s9
	s_sub_i32 s13, 0, s9
	s_mul_i32 s5, s5, s21
	s_sub_i32 s10, s20, s5
	v_rcp_iflag_f32_e32 v0, v0
	s_abs_i32 s12, s10
	s_xor_b32 s11, s10, s8
	s_ashr_i32 s11, s11, 31
	v_mul_f32_e32 v0, 0x4f7ffffe, v0
	v_cvt_u32_f32_e32 v0, v0
	s_nop 0
	v_mov_b32_e32 v137, v169
	v_readfirstlane_b32 s16, v0
	s_mul_i32 s13, s13, s16
	s_mul_hi_u32 s13, s16, s13
	s_add_i32 s16, s16, s13
	s_mul_hi_u32 s13, s12, s16
	s_mul_i32 s16, s13, s9
	s_sub_i32 s12, s12, s16
	s_add_i32 s16, s13, 1
	s_sub_i32 s17, s12, s9
	s_cmp_ge_u32 s12, s9
	s_cselect_b32 s13, s16, s13
	s_cselect_b32 s12, s17, s12
	s_add_i32 s16, s13, 1
	s_cmp_ge_u32 s12, s9
	s_cselect_b32 s9, s16, s13
	s_xor_b32 s9, s9, s11
	s_sub_i32 s9, s9, s11
	s_mul_i32 s58, s9, s8
	s_sub_i32 s8, s10, s58
	s_add_i32 s8, s8, s4
	s_lshl_b32 s43, s8, 8
	s_nop 0
	v_ashrrev_i32_e32 v141, 3, v137
	s_nop 0
	v_lshrrev_b32_e32 v5, 2, v141
	s_ashr_i32 s4, s43, 31
	s_lshl_b32 s12, s9, 8
	v_lshlrev_b32_e32 v140, 4, v137
	v_lshrrev_b32_e32 v2, 1, v137
	v_and_b32_e32 v133, 0x7fffffe0, v141
	v_and_b32_e32 v134, 4, v5
	s_mul_i32 s4, s66, s4
	s_mul_hi_u32 s8, s66, s43
	v_bfe_u32 v132, v140, 6, 2
	v_or_b32_e32 v5, v134, v133
	v_and_b32_e32 v158, 24, v2
	s_add_i32 s4, s8, s4
	s_mul_i32 s8, s67, s43
	s_ashr_i32 s13, s12, 31
	v_readfirstlane_b32 s46, v137
	v_and_b32_e32 v131, 32, v2
	v_or3_b32 v2, v5, v158, v132
	v_add_u32_e32 v5, 0x2000, v140
	s_add_i32 s11, s4, s8
	s_mul_i32 s4, s30, s13
	s_mul_hi_u32 s8, s30, s12
	v_and_b32_e32 v0, 32, v137
	v_ashrrev_i32_e32 v142, 7, v5
	s_ashr_i32 s57, s46, 6
	s_add_i32 s4, s8, s4
	s_mul_i32 s8, s31, s12
	s_ashr_i32 s52, s46, 8
	v_bitop3_b32 v0, v140, v0, 48 bitop3:0x6c
	v_lshrrev_b32_e32 v5, 2, v142
	s_lshl_b32 s16, s57, 10
	s_add_i32 s4, s4, s8
	s_mul_i32 s53, s30, s12
	v_bfe_u32 v3, v137, 2, 26
	v_lshrrev_b32_e32 v130, 1, v0
	v_and_b32_e32 v135, 0x7fffffe0, v142
	v_and_b32_e32 v136, 4, v5
	s_add_u32 s8, s60, s53
	v_or_b32_e32 v4, v130, v131
	v_bfi_b32 v0, 15, v3, v141
	v_mul_lo_u32 v2, v2, s18
	v_bfi_b32 v3, -16, v142, v3
	v_or_b32_e32 v5, v135, v136
	s_addc_u32 s9, s61, s4
	s_add_i32 s69, s16, 16
	v_add_lshl_u32 v2, v2, v4, 1
	v_or3_b32 v5, v5, v158, v132
	v_mul_lo_u32 v3, v3, s96
	s_add_i32 m0, s69, 0x10000
	v_mul_lo_u32 v0, v0, s96
	v_add_lshl_u32 v138, v3, v4, 1
	v_mul_lo_u32 v3, v5, s18
	s_mul_i32 s10, s66, s43
	global_load_lds_dwordx4 v2, s[8:9]
	s_add_i32 m0, s69, 0x12000
	v_add_lshl_u32 v0, v0, v4, 1
	v_add_lshl_u32 v4, v3, v4, 1
	s_add_u32 s10, s40, s10
	global_load_lds_dwordx4 v4, s[8:9]
	s_addc_u32 s11, s41, s11
	s_mov_b32 m0, s69
	s_add_i32 s17, s69, 0x2000
	global_load_lds_dwordx4 v0, s[10:11]
	s_mov_b32 m0, s17
	s_add_u32 s82, s8, s64
	global_load_lds_dwordx4 v138, s[10:11]
	s_addc_u32 s83, s9, s65
	s_add_i32 m0, s69, 0x14000
	s_nop 0
	global_load_lds_dwordx4 v2, s[82:83]
	s_add_i32 m0, s69, 0x16000
	s_add_u32 s44, s10, s26
	s_addc_u32 s45, s11, s27
	s_add_i32 s34, s69, 0x4000
	global_load_lds_dwordx4 v4, s[82:83]
	s_mov_b32 m0, s34
	s_add_i32 s81, s69, 0x6000
	global_load_lds_dwordx4 v0, s[44:45]
	s_mov_b32 m0, s81
	s_cmp_lg_u32 s52, 1
	global_load_lds_dwordx4 v138, s[44:45]
	s_cbranch_scc1 .LBB0_412
	s_barrier
